# context Hyena items rewritten: all 18 A and 8 B fragments requested at once (was a chain of load-wait-MFMA), transposed z epilogue like the latent items; 256 extra tiles in the S4 transpose pass
# speedup vs baseline: 1.0138x; 1.0138x over previous
; DI void hyena_item(const Params& p, int l, int it) {
;     ...
;   if (it < 2048) { c = it >> 3; f = l; L = 2048; posoff = CTXL; tt0 = (it & 7) * 256 + w * 64; ntile = 32; }
;   else { c = it - 2048; f = 2; L = 256; posoff = 0; tt0 = w * 64; ntile = 4; }
;   const u16* R0 = WSP(const u16, OFF_RF) + ((size_t)(f * 256 + c) * 2) * RSTR;
;   const u16* R1 = R0 + RSTR;
;   const u16* UT = WSP(const u16, OFF_UT);
;   const int l16 = lane & 15, kg = lane >> 4;
;   f32x4 acc[4];
; #pragma unroll
;   for (int i = 0; i < 4; ++i) acc[i] = (f32x4){0.f, 0.f, 0.f, 0.f};
;   const u16* ub = UT + ((size_t)(c * 16 + l16)) * TPB + posoff + kg * 8;
;   const u16* rsel = (l16 & 1) ? (R1 - 1) : R0;
;   const int nb = L - (tt0 + l16) + kg * 8;
;   for (int s0 = 0; s0 < L; s0 += 32) {
;     const bf16x8 bfrag = *(const bf16x8*)(ub + s0);
; #pragma unroll
;     for (int i = 0; i < 4; ++i) {
;       const u32* ap = (const u32*)(rsel + (nb - 16 * i + s0));
;       union { u32 u[4]; bf16x8 v; } au;
;       au.u[0] = ap[0]; au.u[1] = ap[1]; au.u[2] = ap[2]; au.u[3] = ap[3];
;       acc[i] = __builtin_amdgcn_mfma_f32_16x16x32_bf16(au.v, bfrag, acc[i], 0, 0, 0);
;     }
;   }
;   float ssq = 0.f;
;   for (int t = 0; t < ntile; ++t) ssq += WSP(const float, OFF_PART)[(size_t)(f * 32 + t) * 256 + c];
;   const float scale = rsqrtf(ssq + EPSF);
;   const float bias = p.in[I_HYBIAS][l * 256 + c];
.LBB0_1133:
	s_or_b64 exec, exec, s[34:35]
	v_readlane_b32 s13, v254, 1
	s_waitcnt lgkmcnt(0)
	s_barrier
	v_mov_b32_e32 v0, s13
	ds_read_b32 v0, v0
	s_mov_b64 s[34:35], -1
	s_waitcnt lgkmcnt(0)
	s_barrier
	v_cmp_le_i32_e32 vcc, s41, v0
	v_readfirstlane_b32 s45, v0
	s_cbranch_vccnz .LBB0_1128
	s_cmp_ge_i32 s45, s40
	s_cbranch_scc0 .LBB0_1142
	s_sub_i32 s13, s45, s40
	s_cmpk_gt_i32 s13, 0x3ff
	s_cbranch_scc0 .LBB0_1137
	v_and_b32_e32 v17, 15, v218
	v_and_b32_e32 v16, 0xffffffc0, v218
	v_bfe_u32 v22, v218, 4, 2
	s_add_i32 s36, s13, 0xfffffc00
	s_add_i32 s38, s13, 0x400
	v_lshl_or_b32 v1, s36, 4, v17
	s_movk_i32 s16, 0x900
	s_mul_i32 s86, s38, 0x2020
	v_mul_lo_u32 v172, v1, s16
	v_readlane_b32 s16, v255, 50
	s_lshl_b64 s[34:35], s[86:87], 1
	v_readlane_b32 s17, v255, 51
	s_add_u32 s34, s96, s34
	s_addc_u32 s35, s97, s35
	s_nop 2
	v_lshl_add_u64 v[18:19], v[172:173], 1, s[16:17]
	v_lshlrev_b32_e32 v172, 4, v22
	v_lshl_add_u64 v[2:3], v[18:19], 0, v[172:173]
	v_bfe_i32 v0, v218, 0, 1
	v_and_b32_e32 v172, 0x201e, v0
	v_lshl_add_u64 v[0:1], s[34:35], 0, v[172:173]
	s_mov_b64 s[34:35], 0x199c8000
	v_lshl_add_u64 v[0:1], v[0:1], 0, s[34:35]
	v_lshlrev_b32_e32 v4, 3, v22
	v_sub_u32_e32 v4, v4, v16
	v_add_u32_e32 v4, 0x100, v4
	v_sub_u32_e32 v6, v4, v17
	v_ashrrev_i32_e32 v7, 31, v6
	v_lshl_add_u64 v[6:7], v[6:7], 1, v[0:1]
	global_load_dwordx4 v[32:35], v[6:7], off offset:-96
	global_load_dwordx4 v[36:39], v[6:7], off offset:-64
	global_load_dwordx4 v[40:43], v[6:7], off offset:-32
	global_load_dwordx4 v[44:47], v[6:7], off
	global_load_dwordx4 v[48:51], v[6:7], off offset:32
	global_load_dwordx4 v[52:55], v[6:7], off offset:64
	global_load_dwordx4 v[56:59], v[6:7], off offset:96
	global_load_dwordx4 v[60:63], v[6:7], off offset:128
	global_load_dwordx4 v[64:67], v[6:7], off offset:160
	global_load_dwordx4 v[68:71], v[6:7], off offset:192
	global_load_dwordx4 v[72:75], v[6:7], off offset:224
	global_load_dwordx4 v[76:79], v[6:7], off offset:256
	global_load_dwordx4 v[80:83], v[6:7], off offset:288
	global_load_dwordx4 v[84:87], v[6:7], off offset:320
	global_load_dwordx4 v[88:91], v[6:7], off offset:352
	global_load_dwordx4 v[92:95], v[6:7], off offset:384
	global_load_dwordx4 v[96:99], v[6:7], off offset:416
	global_load_dwordx4 v[100:103], v[6:7], off offset:448
	global_load_dwordx4 v[104:107], v[2:3], off
	global_load_dwordx4 v[108:111], v[2:3], off offset:64
	global_load_dwordx4 v[112:115], v[2:3], off offset:128
	global_load_dwordx4 v[116:119], v[2:3], off offset:192
	global_load_dwordx4 v[120:123], v[2:3], off offset:256
	global_load_dwordx4 v[124:127], v[2:3], off offset:320
	global_load_dwordx4 v[128:131], v[2:3], off offset:384
	global_load_dwordx4 v[132:135], v[2:3], off offset:448
	s_mov_b32 s39, s87
	s_lshl_b64 s[34:35], s[38:39], 2
	v_readlane_b32 s16, v254, 45
	v_readlane_b32 s17, v254, 46
	s_add_u32 s34, s16, s34
	s_addc_u32 s35, s17, s35
	v_mov_b32_e32 v149, 0xe000
	global_load_dword v144, v149, s[34:35]
	global_load_dword v145, v149, s[34:35] offset:1024
	global_load_dword v146, v149, s[34:35] offset:2048
	global_load_dword v147, v149, s[34:35] offset:3072
	s_add_i32 s86, s36, s42
	s_lshl_b64 s[34:35], s[86:87], 2
	v_readlane_b32 s18, v254, 31
	v_readlane_b32 s19, v254, 32
	s_add_u32 s34, s18, s34
	s_addc_u32 s35, s19, s35
	global_load_dword v148, v173, s[34:35]
	v_lshl_add_u32 v25, v22, 2, v16
	v_mov_b32_e32 v27, 0
	v_lshlrev_b32_e32 v26, 1, v25
	v_lshl_add_u64 v[28:29], v[18:19], 0, v[26:27]
	global_load_dwordx2 v[136:137], v[28:29], off
	global_load_dwordx2 v[138:139], v[28:29], off offset:32
	global_load_dwordx2 v[140:141], v[28:29], off offset:64
	global_load_dwordx2 v[142:143], v[28:29], off offset:96
	v_mov_b64_e32 v[0:1], 0
	v_mov_b64_e32 v[2:3], 0
	v_mov_b64_e32 v[4:5], 0
	v_mov_b64_e32 v[6:7], 0
	v_mov_b64_e32 v[8:9], 0
	v_mov_b64_e32 v[10:11], 0
	v_mov_b64_e32 v[12:13], 0
	v_mov_b64_e32 v[14:15], 0
	v_lshlrev_b32_e32 v30, 10, v17
	v_lshl_add_u32 v30, v25, 2, v30
	s_lshl_b32 s16, s36, 14
	s_add_u32 s16, s16, 0x2000000
	s_add_u32 s16, s96, s16
	s_addc_u32 s17, s97, 0
	s_waitcnt vmcnt(16)
	v_mfma_f32_16x16x32_bf16 v[0:3], v[44:47], v[104:107], v[0:3]
	v_mfma_f32_16x16x32_bf16 v[4:7], v[40:43], v[104:107], v[4:7]
	v_mfma_f32_16x16x32_bf16 v[8:11], v[36:39], v[104:107], v[8:11]
	v_mfma_f32_16x16x32_bf16 v[12:15], v[32:35], v[104:107], v[12:15]
	s_waitcnt vmcnt(15)
; DI u16 f2bf(float x) { u32 u = __float_as_uint(x); u += 0x7fffu + ((u >> 16) & 1u); return (u16)(u >> 16); }
; DI float bf2f(u16 v) { return __uint_as_float(((u32)v) << 16); }
; DI void hyena_item(const Params& p, int l, int it) {
;     ...
;   for (int s0 = 0; s0 < L; s0 += 32) {
;     const bf16x8 bfrag = *(const bf16x8*)(ub + s0);
; #pragma unroll
;     for (int i = 0; i < 4; ++i) {
;       const u32* ap = (const u32*)(rsel + (nb - 16 * i + s0));
;       union { u32 u[4]; bf16x8 v; } au;
;       au.u[0] = ap[0]; au.u[1] = ap[1]; au.u[2] = ap[2]; au.u[3] = ap[3];
;       acc[i] = __builtin_amdgcn_mfma_f32_16x16x32_bf16(au.v, bfrag, acc[i], 0, 0, 0);
;     }
;   }
;   float ssq = 0.f;
;   for (int t = 0; t < ntile; ++t) ssq += WSP(const float, OFF_PART)[(size_t)(f * 32 + t) * 256 + c];
;   const float scale = rsqrtf(ssq + EPSF);
;   const float bias = p.in[I_HYBIAS][l * 256 + c];
;   const u16* X1C = WSP(const u16, OFF_X1C);
;   u16* YM = WSP(u16, OFF_ACT);
;   const int b = l16;
; #pragma unroll
;   for (int i = 0; i < 4; ++i)
; #pragma unroll
;     for (int r = 0; r < 4; ++r) {
;       const int t = tt0 + 16 * i + kg * 4 + r;
;       const size_t row = (size_t)b * TPB + posoff + t;
;       const float u = bf2f(UT[((size_t)(c * 16 + b)) * TPB + posoff + t]);
;       const float x1 = bf2f(X1C[row * 256 + c]);
;       YM[row * 1024 + c] = f2bf(x1 * (scale * acc[i][r] + bias * u));
;     }
	v_mfma_f32_16x16x32_bf16 v[0:3], v[52:55], v[108:111], v[0:3]
	v_mfma_f32_16x16x32_bf16 v[4:7], v[48:51], v[108:111], v[4:7]
	v_mfma_f32_16x16x32_bf16 v[8:11], v[44:47], v[108:111], v[8:11]
	v_mfma_f32_16x16x32_bf16 v[12:15], v[40:43], v[108:111], v[12:15]
	s_waitcnt vmcnt(14)
	v_mfma_f32_16x16x32_bf16 v[0:3], v[60:63], v[112:115], v[0:3]
	v_mfma_f32_16x16x32_bf16 v[4:7], v[56:59], v[112:115], v[4:7]
	v_mfma_f32_16x16x32_bf16 v[8:11], v[52:55], v[112:115], v[8:11]
	v_mfma_f32_16x16x32_bf16 v[12:15], v[48:51], v[112:115], v[12:15]
	s_waitcnt vmcnt(13)
	v_mfma_f32_16x16x32_bf16 v[0:3], v[68:71], v[116:119], v[0:3]
	v_mfma_f32_16x16x32_bf16 v[4:7], v[64:67], v[116:119], v[4:7]
	v_mfma_f32_16x16x32_bf16 v[8:11], v[60:63], v[116:119], v[8:11]
	v_mfma_f32_16x16x32_bf16 v[12:15], v[56:59], v[116:119], v[12:15]
	s_waitcnt vmcnt(12)
	v_mfma_f32_16x16x32_bf16 v[0:3], v[76:79], v[120:123], v[0:3]
	v_mfma_f32_16x16x32_bf16 v[4:7], v[72:75], v[120:123], v[4:7]
	v_mfma_f32_16x16x32_bf16 v[8:11], v[68:71], v[120:123], v[8:11]
	v_mfma_f32_16x16x32_bf16 v[12:15], v[64:67], v[120:123], v[12:15]
	s_waitcnt vmcnt(11)
	v_mfma_f32_16x16x32_bf16 v[0:3], v[84:87], v[124:127], v[0:3]
	v_mfma_f32_16x16x32_bf16 v[4:7], v[80:83], v[124:127], v[4:7]
	v_mfma_f32_16x16x32_bf16 v[8:11], v[76:79], v[124:127], v[8:11]
	v_mfma_f32_16x16x32_bf16 v[12:15], v[72:75], v[124:127], v[12:15]
	s_waitcnt vmcnt(10)
	v_mfma_f32_16x16x32_bf16 v[0:3], v[92:95], v[128:131], v[0:3]
	v_mfma_f32_16x16x32_bf16 v[4:7], v[88:91], v[128:131], v[4:7]
	v_mfma_f32_16x16x32_bf16 v[8:11], v[84:87], v[128:131], v[8:11]
	v_mfma_f32_16x16x32_bf16 v[12:15], v[80:83], v[128:131], v[12:15]
	s_waitcnt vmcnt(9)
	v_mfma_f32_16x16x32_bf16 v[0:3], v[100:103], v[132:135], v[0:3]
	v_mfma_f32_16x16x32_bf16 v[4:7], v[96:99], v[132:135], v[4:7]
	v_mfma_f32_16x16x32_bf16 v[8:11], v[92:95], v[132:135], v[8:11]
	v_mfma_f32_16x16x32_bf16 v[12:15], v[88:91], v[132:135], v[12:15]
	s_waitcnt vmcnt(0)
	v_add_f32_e32 v20, 0, v144
	v_add_f32_e32 v20, v20, v145
	v_add_f32_e32 v20, v20, v146
	v_add_f32_e32 v20, v20, v147
	s_mov_b32 s18, 0x800000
	v_add_f32_e32 v20, 0x358637bd, v20
	v_cmp_gt_f32_e32 vcc, s18, v20
	v_mul_f32_e32 v21, 0x4b800000, v20
	s_nop 1
	v_cndmask_b32_e32 v20, v20, v21, vcc
	v_rsq_f32_e32 v20, v20
	s_nop 0
	v_mul_f32_e32 v21, 0x45800000, v20
	v_cndmask_b32_e32 v20, v20, v21, vcc
	s_nop 4
	v_lshlrev_b32_e32 v21, 16, v136
	v_mul_f32_e32 v21, v148, v21
	v_fmac_f32_e32 v21, v0, v20
	v_mov_b32_e32 v0, v21
	v_and_b32_e32 v21, 0xffff0000, v136
	v_mul_f32_e32 v21, v148, v21
	v_fmac_f32_e32 v21, v1, v20
	v_mov_b32_e32 v1, v21
	v_lshlrev_b32_e32 v21, 16, v137
	v_mul_f32_e32 v21, v148, v21
	v_fmac_f32_e32 v21, v2, v20
	v_mov_b32_e32 v2, v21
	v_and_b32_e32 v21, 0xffff0000, v137
	v_mul_f32_e32 v21, v148, v21
	v_fmac_f32_e32 v21, v3, v20
	v_mov_b32_e32 v3, v21
	v_lshlrev_b32_e32 v21, 16, v138
	v_mul_f32_e32 v21, v148, v21
	v_fmac_f32_e32 v21, v4, v20
	v_mov_b32_e32 v4, v21
	v_and_b32_e32 v21, 0xffff0000, v138
	v_mul_f32_e32 v21, v148, v21
	v_fmac_f32_e32 v21, v5, v20
	v_mov_b32_e32 v5, v21
	v_lshlrev_b32_e32 v21, 16, v139
	v_mul_f32_e32 v21, v148, v21
	v_fmac_f32_e32 v21, v6, v20
	v_mov_b32_e32 v6, v21
	v_and_b32_e32 v21, 0xffff0000, v139
	v_mul_f32_e32 v21, v148, v21
	v_fmac_f32_e32 v21, v7, v20
	v_mov_b32_e32 v7, v21
	v_lshlrev_b32_e32 v21, 16, v140
	v_mul_f32_e32 v21, v148, v21
	v_fmac_f32_e32 v21, v8, v20
	v_mov_b32_e32 v8, v21
	v_and_b32_e32 v21, 0xffff0000, v140
	v_mul_f32_e32 v21, v148, v21
	v_fmac_f32_e32 v21, v9, v20
	v_mov_b32_e32 v9, v21
	v_lshlrev_b32_e32 v21, 16, v141
	v_mul_f32_e32 v21, v148, v21
	v_fmac_f32_e32 v21, v10, v20
	v_mov_b32_e32 v10, v21
	v_and_b32_e32 v21, 0xffff0000, v141
	v_mul_f32_e32 v21, v148, v21
	v_fmac_f32_e32 v21, v11, v20
	v_mov_b32_e32 v11, v21
	v_lshlrev_b32_e32 v21, 16, v142
	v_mul_f32_e32 v21, v148, v21
	v_fmac_f32_e32 v21, v12, v20
	v_mov_b32_e32 v12, v21
	v_and_b32_e32 v21, 0xffff0000, v142
	v_mul_f32_e32 v21, v148, v21
	v_fmac_f32_e32 v21, v13, v20
	v_mov_b32_e32 v13, v21
	v_lshlrev_b32_e32 v21, 16, v143
	v_mul_f32_e32 v21, v148, v21
	v_fmac_f32_e32 v21, v14, v20
	v_mov_b32_e32 v14, v21
	v_and_b32_e32 v21, 0xffff0000, v143
	v_mul_f32_e32 v21, v148, v21
	v_fmac_f32_e32 v21, v15, v20
	v_mov_b32_e32 v15, v21
	global_store_dwordx4 v30, v[0:3], s[16:17]
	global_store_dwordx4 v30, v[4:7], s[16:17] offset:64
	global_store_dwordx4 v30, v[8:11], s[16:17] offset:128
	global_store_dwordx4 v30, v[12:15], s[16:17] offset:192
	s_mov_b32 s24, s64
	v_readlane_b32 s18, v254, 10
	v_readlane_b32 s19, v254, 11
	s_mov_b64 s[34:35], 0

; DI u32 pack2(float a, float b) { return (u32)f2bf(a) | ((u32)f2bf(b) << 16); }
; DI float bflo(u32 v) { return __uint_as_float(v << 16); }
; DI float bfhi(u32 v) { return __uint_as_float(v & 0xffff0000u); }
; DI float silu_f(float x) { return x / (1.f + __expf(-x)); }
; DI void phase_ssd_combine(const Params& p, int l, int bid, int nblk) {
;     ...
;   for (int row = bid * 4 + w; row < ROWS; row += nblk * 4) {
;     const int pos = row % TPB;
;     if (l == 1 && pos < CTXL) continue;
;     const uint4 vf = *(const uint4*)(YF + (size_t)row * 512 + c0);
;     const uint4 vb = *(const uint4*)(YB + (size_t)row * 512 + c0);
;     const uint4 vx = *(const uint4*)(XBCA + (size_t)row * 1024 + c0);
;     const uint4 vz = *(const uint4*)(PZ + (size_t)row * 512 + c0);
;     const u32 af_[4] = {vf.x, vf.y, vf.z, vf.w}, ab_[4] = {vb.x, vb.y, vb.z, vb.w};
;     const u32 ax_[4] = {vx.x, vx.y, vx.z, vx.w}, az_[4] = {vz.x, vz.y, vz.z, vz.w};
;     float y[8];
;     float ss = 0.f;
; #pragma unroll
;     for (int i = 0; i < 4; ++i) {
;       const float y0 = bflo(af_[i]) + bflo(ab_[i]) + dsk * bflo(ax_[i]);
;       const float y1 = bfhi(af_[i]) + bfhi(ab_[i]) + dsk * bfhi(ax_[i]);
;       y[2 * i] = y0 * silu_f(bflo(az_[i]));
;       y[2 * i + 1] = y1 * silu_f(bfhi(az_[i]));
;       ss += y[2 * i] * y[2 * i] + y[2 * i + 1] * y[2 * i + 1];
;     }
; #pragma unroll
;     for (int o = 16; o >= 1; o >>= 1) ss += __shfl_xor(ss, o);
;     const float rs = rsqrtf(ss * (1.f / 256.f) + EPSF);
;     float o8[8];
; #pragma unroll
;     for (int i = 0; i < 8; ++i) o8[i] = y[i] * rs * ng[c0 + i];
;     uint4 o = {pack2(o8[0], o8[1]), pack2(o8[2], o8[3]), pack2(o8[4], o8[5]), pack2(o8[6], o8[7])};
;     *(uint4*)&YM[(size_t)row * 1024 + 256 + c0] = o;
.Lcmb_top:
	s_waitcnt vmcnt(5)
	v_lshlrev_b32_e32 v64, 16, v32
	v_and_b32_e32 v65, 0xffff0000, v32
	v_lshlrev_b32_e32 v66, 16, v33
	v_and_b32_e32 v67, 0xffff0000, v33
	v_lshlrev_b32_e32 v68, 16, v34
	v_and_b32_e32 v69, 0xffff0000, v34
	v_lshlrev_b32_e32 v70, 16, v35
	v_and_b32_e32 v71, 0xffff0000, v35
	v_lshlrev_b32_e32 v80, 16, v36
	v_and_b32_e32 v81, 0xffff0000, v36
	v_lshlrev_b32_e32 v82, 16, v37
	v_and_b32_e32 v83, 0xffff0000, v37
	v_lshlrev_b32_e32 v84, 16, v38
	v_and_b32_e32 v85, 0xffff0000, v38
	v_lshlrev_b32_e32 v86, 16, v39
	v_and_b32_e32 v87, 0xffff0000, v39
	v_add_f32_e32 v64, v64, v80
	v_add_f32_e32 v65, v65, v81
	v_add_f32_e32 v66, v66, v82
	v_add_f32_e32 v67, v67, v83
	v_add_f32_e32 v68, v68, v84
	v_add_f32_e32 v69, v69, v85
	v_add_f32_e32 v70, v70, v86
	v_add_f32_e32 v71, v71, v87
	v_lshlrev_b32_e32 v80, 16, v40
	v_and_b32_e32 v81, 0xffff0000, v40
	v_lshlrev_b32_e32 v82, 16, v41
	v_and_b32_e32 v83, 0xffff0000, v41
	v_lshlrev_b32_e32 v84, 16, v42
	v_and_b32_e32 v85, 0xffff0000, v42
	v_lshlrev_b32_e32 v86, 16, v43
	v_and_b32_e32 v87, 0xffff0000, v43
	v_fmac_f32_e32 v64, v24, v80
	v_fmac_f32_e32 v65, v24, v81
	v_fmac_f32_e32 v66, v24, v82
	v_fmac_f32_e32 v67, v24, v83
	v_fmac_f32_e32 v68, v24, v84
	v_fmac_f32_e32 v69, v24, v85
	v_fmac_f32_e32 v70, v24, v86
	v_fmac_f32_e32 v71, v24, v87
	v_lshlrev_b32_e32 v72, 16, v44
	v_and_b32_e32 v73, 0xffff0000, v44
	v_lshlrev_b32_e32 v74, 16, v45
	v_and_b32_e32 v75, 0xffff0000, v45
	v_lshlrev_b32_e32 v76, 16, v46
	v_and_b32_e32 v77, 0xffff0000, v46
	v_lshlrev_b32_e32 v78, 16, v47
	v_and_b32_e32 v79, 0xffff0000, v47
	v_mul_f32_e32 v80, 0xbfb8aa3b, v72
	v_mul_f32_e32 v81, 0xbfb8aa3b, v73
	v_mul_f32_e32 v82, 0xbfb8aa3b, v74
	v_mul_f32_e32 v83, 0xbfb8aa3b, v75
	v_mul_f32_e32 v84, 0xbfb8aa3b, v76
	v_mul_f32_e32 v85, 0xbfb8aa3b, v77
	v_mul_f32_e32 v86, 0xbfb8aa3b, v78
	v_mul_f32_e32 v87, 0xbfb8aa3b, v79
	v_exp_f32_e32 v80, v80
	v_exp_f32_e32 v81, v81
	v_exp_f32_e32 v82, v82
	v_exp_f32_e32 v83, v83
	v_exp_f32_e32 v84, v84
	v_exp_f32_e32 v85, v85
	v_exp_f32_e32 v86, v86
	v_exp_f32_e32 v87, v87
	v_add_f32_e32 v80, 1.0, v80
	v_add_f32_e32 v81, 1.0, v81
	v_add_f32_e32 v82, 1.0, v82
	v_add_f32_e32 v83, 1.0, v83
	v_add_f32_e32 v84, 1.0, v84
	v_add_f32_e32 v85, 1.0, v85
	v_add_f32_e32 v86, 1.0, v86
	v_add_f32_e32 v87, 1.0, v87
	v_rcp_f32_e32 v80, v80
	v_rcp_f32_e32 v81, v81
	v_rcp_f32_e32 v82, v82
	v_rcp_f32_e32 v83, v83
	v_rcp_f32_e32 v84, v84
	v_rcp_f32_e32 v85, v85
	v_rcp_f32_e32 v86, v86
	v_rcp_f32_e32 v87, v87
	v_mul_f32_e32 v72, v72, v80
	v_mul_f32_e32 v73, v73, v81
	v_mul_f32_e32 v74, v74, v82
	v_mul_f32_e32 v75, v75, v83
	v_mul_f32_e32 v76, v76, v84
	v_mul_f32_e32 v77, v77, v85
	v_mul_f32_e32 v78, v78, v86
	v_mul_f32_e32 v79, v79, v87
	v_mul_f32_e32 v64, v64, v72
	v_mul_f32_e32 v65, v65, v73
	v_mul_f32_e32 v66, v66, v74
	v_mul_f32_e32 v67, v67, v75
	v_mul_f32_e32 v68, v68, v76
	v_mul_f32_e32 v69, v69, v77
	v_mul_f32_e32 v70, v70, v78
	v_mul_f32_e32 v71, v71, v79
	v_mul_f32_e32 v7, v64, v64
	v_fmac_f32_e32 v7, v65, v65
	v_fmac_f32_e32 v7, v66, v66
	v_fmac_f32_e32 v7, v67, v67
	v_fmac_f32_e32 v7, v68, v68
	v_fmac_f32_e32 v7, v69, v69
	v_fmac_f32_e32 v7, v70, v70
	v_fmac_f32_e32 v7, v71, v71
	s_nop 1
	v_add_f32_dpp v7, v7, v7 quad_perm:[1,0,3,2] row_mask:0xf bank_mask:0xf
	s_nop 1
	v_add_f32_dpp v7, v7, v7 quad_perm:[2,3,0,1] row_mask:0xf bank_mask:0xf
	s_nop 1
	v_add_f32_dpp v7, v7, v7 row_half_mirror row_mask:0xf bank_mask:0xf
	s_nop 1
	v_add_f32_dpp v7, v7, v7 row_mirror row_mask:0xf bank_mask:0xf
	s_nop 1
	ds_bpermute_b32 v8, v5, v7
	s_waitcnt lgkmcnt(0)
	v_add_f32_e32 v7, v7, v8
	v_mov_b32_e32 v8, 0x358637bd
	v_fmac_f32_e32 v8, 0x3b800000, v7
	v_rsq_f32_e32 v8, v8
	s_nop 0
	v_mul_f32_e32 v64, v64, v8
	v_mul_f32_e32 v65, v65, v8
	v_mul_f32_e32 v66, v66, v8
	v_mul_f32_e32 v67, v67, v8
	v_mul_f32_e32 v68, v68, v8
	v_mul_f32_e32 v69, v69, v8
	v_mul_f32_e32 v70, v70, v8
	v_mul_f32_e32 v71, v71, v8
	v_mul_f32_e32 v64, v64, v16
	v_mul_f32_e32 v65, v65, v17
	v_mul_f32_e32 v66, v66, v18
	v_mul_f32_e32 v67, v67, v19
	v_mul_f32_e32 v68, v68, v20
	v_mul_f32_e32 v69, v69, v21
	v_mul_f32_e32 v70, v70, v22
	v_mul_f32_e32 v71, v71, v23
	v_cvt_pk_bf16_f32 v88, v64, v65
	v_cvt_pk_bf16_f32 v89, v66, v67
	v_cvt_pk_bf16_f32 v90, v68, v69
	v_cvt_pk_bf16_f32 v91, v70, v71
	s_nop 0
	global_store_dwordx4 v4, v[88:91], s[80:81] offset:512
	s_add_i32 s28, s27, 2
	s_cmp_lt_u32 s28, s26
	s_cselect_b32 s28, s28, 0
	s_cmp_ge_u32 s28, s23
	s_addc_u32 s44, s28, 0
	s_cmp_ge_u32 s44, s25
	s_addc_u32 s44, s44, 0
	s_lshl_b32 s44, s44, 11
	s_add_i32 s44, s44, s19
	s_lshl_b32 s16, s44, 10
	s_lshl_b32 s17, s44, 11
	s_add_u32 s30, s96, s16
	s_addc_u32 s31, s97, 0
	s_add_u32 s48, s30, 0x3600000
	s_addc_u32 s49, s31, 0
	s_add_u32 s30, s30, 0x5a00000
	s_addc_u32 s31, s31, 0
	s_add_u32 s38, s30, 0x2400000
	s_addc_u32 s39, s31, 0
	s_add_u32 s66, s96, s17
	s_addc_u32 s67, s97, 0
	s_add_u32 s66, s66, 0xea00000
	s_addc_u32 s67, s67, 0
	s_add_u32 s80, s6, s17
	s_addc_u32 s81, s7, 0
	global_load_dwordx4 v[32:35], v4, s[30:31]
	global_load_dwordx4 v[36:39], v4, s[38:39]
	global_load_dwordx4 v[40:43], v4, s[66:67]
	global_load_dwordx4 v[44:47], v4, s[48:49]
	s_waitcnt vmcnt(5)
; DI u32 pack2(float a, float b) { return (u32)f2bf(a) | ((u32)f2bf(b) << 16); }
; DI float bflo(u32 v) { return __uint_as_float(v << 16); }
; DI float bfhi(u32 v) { return __uint_as_float(v & 0xffff0000u); }
; DI float silu_f(float x) { return x / (1.f + __expf(-x)); }
; DI void phase_ssd_combine(const Params& p, int l, int bid, int nblk) {
;     ...
;     const uint4 vf = *(const uint4*)(YF + (size_t)row * 512 + c0);
;     const uint4 vb = *(const uint4*)(YB + (size_t)row * 512 + c0);
;     const uint4 vx = *(const uint4*)(XBCA + (size_t)row * 1024 + c0);
;     const uint4 vz = *(const uint4*)(PZ + (size_t)row * 512 + c0);
;     const u32 af_[4] = {vf.x, vf.y, vf.z, vf.w}, ab_[4] = {vb.x, vb.y, vb.z, vb.w};
;     const u32 ax_[4] = {vx.x, vx.y, vx.z, vx.w}, az_[4] = {vz.x, vz.y, vz.z, vz.w};
;     float y[8];
;     float ss = 0.f;
; #pragma unroll
;     for (int i = 0; i < 4; ++i) {
;       const float y0 = bflo(af_[i]) + bflo(ab_[i]) + dsk * bflo(ax_[i]);
;       const float y1 = bfhi(af_[i]) + bfhi(ab_[i]) + dsk * bfhi(ax_[i]);
;       y[2 * i] = y0 * silu_f(bflo(az_[i]));
;       y[2 * i + 1] = y1 * silu_f(bfhi(az_[i]));
;       ss += y[2 * i] * y[2 * i] + y[2 * i + 1] * y[2 * i + 1];
;     }
; #pragma unroll
;     for (int o = 16; o >= 1; o >>= 1) ss += __shfl_xor(ss, o);
;     const float rs = rsqrtf(ss * (1.f / 256.f) + EPSF);
;     float o8[8];
; #pragma unroll
;     for (int i = 0; i < 8; ++i) o8[i] = y[i] * rs * ng[c0 + i];
;     uint4 o = {pack2(o8[0], o8[1]), pack2(o8[2], o8[3]), pack2(o8[4], o8[5]), pack2(o8[6], o8[7])};
;     *(uint4*)&YM[(size_t)row * 1024 + 256 + c0] = o;
	v_lshlrev_b32_e32 v64, 16, v48
	v_and_b32_e32 v65, 0xffff0000, v48
	v_lshlrev_b32_e32 v66, 16, v49
	v_and_b32_e32 v67, 0xffff0000, v49
	v_lshlrev_b32_e32 v68, 16, v50
	v_and_b32_e32 v69, 0xffff0000, v50
	v_lshlrev_b32_e32 v70, 16, v51
	v_and_b32_e32 v71, 0xffff0000, v51
	v_lshlrev_b32_e32 v80, 16, v52
	v_and_b32_e32 v81, 0xffff0000, v52
	v_lshlrev_b32_e32 v82, 16, v53
	v_and_b32_e32 v83, 0xffff0000, v53
	v_lshlrev_b32_e32 v84, 16, v54
	v_and_b32_e32 v85, 0xffff0000, v54
	v_lshlrev_b32_e32 v86, 16, v55
	v_and_b32_e32 v87, 0xffff0000, v55
	v_add_f32_e32 v64, v64, v80
	v_add_f32_e32 v65, v65, v81
	v_add_f32_e32 v66, v66, v82
	v_add_f32_e32 v67, v67, v83
	v_add_f32_e32 v68, v68, v84
	v_add_f32_e32 v69, v69, v85
	v_add_f32_e32 v70, v70, v86
	v_add_f32_e32 v71, v71, v87
	v_lshlrev_b32_e32 v80, 16, v56
	v_and_b32_e32 v81, 0xffff0000, v56
	v_lshlrev_b32_e32 v82, 16, v57
	v_and_b32_e32 v83, 0xffff0000, v57
	v_lshlrev_b32_e32 v84, 16, v58
	v_and_b32_e32 v85, 0xffff0000, v58
	v_lshlrev_b32_e32 v86, 16, v59
	v_and_b32_e32 v87, 0xffff0000, v59
	v_fmac_f32_e32 v64, v24, v80
	v_fmac_f32_e32 v65, v24, v81
	v_fmac_f32_e32 v66, v24, v82
	v_fmac_f32_e32 v67, v24, v83
	v_fmac_f32_e32 v68, v24, v84
	v_fmac_f32_e32 v69, v24, v85
	v_fmac_f32_e32 v70, v24, v86
	v_fmac_f32_e32 v71, v24, v87
	v_lshlrev_b32_e32 v72, 16, v60
	v_and_b32_e32 v73, 0xffff0000, v60
	v_lshlrev_b32_e32 v74, 16, v61
	v_and_b32_e32 v75, 0xffff0000, v61
	v_lshlrev_b32_e32 v76, 16, v62
	v_and_b32_e32 v77, 0xffff0000, v62
	v_lshlrev_b32_e32 v78, 16, v63
	v_and_b32_e32 v79, 0xffff0000, v63
	v_mul_f32_e32 v80, 0xbfb8aa3b, v72
	v_mul_f32_e32 v81, 0xbfb8aa3b, v73
	v_mul_f32_e32 v82, 0xbfb8aa3b, v74
	v_mul_f32_e32 v83, 0xbfb8aa3b, v75
	v_mul_f32_e32 v84, 0xbfb8aa3b, v76
	v_mul_f32_e32 v85, 0xbfb8aa3b, v77
	v_mul_f32_e32 v86, 0xbfb8aa3b, v78
	v_mul_f32_e32 v87, 0xbfb8aa3b, v79
	v_exp_f32_e32 v80, v80
	v_exp_f32_e32 v81, v81
	v_exp_f32_e32 v82, v82
	v_exp_f32_e32 v83, v83
	v_exp_f32_e32 v84, v84
	v_exp_f32_e32 v85, v85
	v_exp_f32_e32 v86, v86
	v_exp_f32_e32 v87, v87
	v_add_f32_e32 v80, 1.0, v80
	v_add_f32_e32 v81, 1.0, v81
	v_add_f32_e32 v82, 1.0, v82
	v_add_f32_e32 v83, 1.0, v83
	v_add_f32_e32 v84, 1.0, v84
	v_add_f32_e32 v85, 1.0, v85
	v_add_f32_e32 v86, 1.0, v86
	v_add_f32_e32 v87, 1.0, v87
	v_rcp_f32_e32 v80, v80
	v_rcp_f32_e32 v81, v81
	v_rcp_f32_e32 v82, v82
	v_rcp_f32_e32 v83, v83
	v_rcp_f32_e32 v84, v84
	v_rcp_f32_e32 v85, v85
	v_rcp_f32_e32 v86, v86
	v_rcp_f32_e32 v87, v87
	v_mul_f32_e32 v72, v72, v80
	v_mul_f32_e32 v73, v73, v81
	v_mul_f32_e32 v74, v74, v82
	v_mul_f32_e32 v75, v75, v83
	v_mul_f32_e32 v76, v76, v84
	v_mul_f32_e32 v77, v77, v85
	v_mul_f32_e32 v78, v78, v86
	v_mul_f32_e32 v79, v79, v87
	v_mul_f32_e32 v64, v64, v72
	v_mul_f32_e32 v65, v65, v73
	v_mul_f32_e32 v66, v66, v74
	v_mul_f32_e32 v67, v67, v75
	v_mul_f32_e32 v68, v68, v76
	v_mul_f32_e32 v69, v69, v77
	v_mul_f32_e32 v70, v70, v78
	v_mul_f32_e32 v71, v71, v79
	v_mul_f32_e32 v7, v64, v64
	v_fmac_f32_e32 v7, v65, v65
	v_fmac_f32_e32 v7, v66, v66
	v_fmac_f32_e32 v7, v67, v67
	v_fmac_f32_e32 v7, v68, v68
	v_fmac_f32_e32 v7, v69, v69
	v_fmac_f32_e32 v7, v70, v70
	v_fmac_f32_e32 v7, v71, v71
	s_nop 1
	v_add_f32_dpp v7, v7, v7 quad_perm:[1,0,3,2] row_mask:0xf bank_mask:0xf
	s_nop 1
	v_add_f32_dpp v7, v7, v7 quad_perm:[2,3,0,1] row_mask:0xf bank_mask:0xf
	s_nop 1
	v_add_f32_dpp v7, v7, v7 row_half_mirror row_mask:0xf bank_mask:0xf
	s_nop 1
	v_add_f32_dpp v7, v7, v7 row_mirror row_mask:0xf bank_mask:0xf
	s_nop 1
	ds_bpermute_b32 v8, v5, v7
	s_waitcnt lgkmcnt(0)
	v_add_f32_e32 v7, v7, v8
	v_mov_b32_e32 v8, 0x358637bd
	v_fmac_f32_e32 v8, 0x3b800000, v7
	v_rsq_f32_e32 v8, v8
	s_nop 0
	v_mul_f32_e32 v64, v64, v8
	v_mul_f32_e32 v65, v65, v8
	v_mul_f32_e32 v66, v66, v8
	v_mul_f32_e32 v67, v67, v8
	v_mul_f32_e32 v68, v68, v8
	v_mul_f32_e32 v69, v69, v8
	v_mul_f32_e32 v70, v70, v8
	v_mul_f32_e32 v71, v71, v8
	v_mul_f32_e32 v64, v64, v16
	v_mul_f32_e32 v65, v65, v17
	v_mul_f32_e32 v66, v66, v18
	v_mul_f32_e32 v67, v67, v19
	v_mul_f32_e32 v68, v68, v20
	v_mul_f32_e32 v69, v69, v21
	v_mul_f32_e32 v70, v70, v22
	v_mul_f32_e32 v71, v71, v23
	v_cvt_pk_bf16_f32 v88, v64, v65
	v_cvt_pk_bf16_f32 v89, v66, v67
	v_cvt_pk_bf16_f32 v90, v68, v69
	v_cvt_pk_bf16_f32 v91, v70, v71
	s_nop 0
	global_store_dwordx4 v4, v[88:91], s[82:83] offset:512
	s_add_i32 s28, s27, 3
	s_cmp_lt_u32 s28, s26
	s_cselect_b32 s28, s28, 0
	s_cmp_ge_u32 s28, s23
	s_addc_u32 s44, s28, 0
	s_cmp_ge_u32 s44, s25
	s_addc_u32 s44, s44, 0
	s_lshl_b32 s44, s44, 11
	s_add_i32 s44, s44, s19
	s_lshl_b32 s16, s44, 10
	s_lshl_b32 s17, s44, 11
	s_add_u32 s30, s96, s16
	s_addc_u32 s31, s97, 0
	s_add_u32 s48, s30, 0x3600000
	s_addc_u32 s49, s31, 0
	s_add_u32 s30, s30, 0x5a00000
	s_addc_u32 s31, s31, 0
	s_add_u32 s38, s30, 0x2400000
	s_addc_u32 s39, s31, 0
	s_add_u32 s66, s96, s17
	s_addc_u32 s67, s97, 0
	s_add_u32 s66, s66, 0xea00000
	s_addc_u32 s67, s67, 0
	s_add_u32 s82, s6, s17
	s_addc_u32 s83, s7, 0
	global_load_dwordx4 v[48:51], v4, s[30:31]
	global_load_dwordx4 v[52:55], v4, s[38:39]
	global_load_dwordx4 v[56:59], v4, s[66:67]
	global_load_dwordx4 v[60:63], v4, s[48:49]
	s_add_i32 s27, s27, 2
	s_cmp_lt_u32 s27, s26
	s_cbranch_scc1 .Lcmb_top
	s_waitcnt vmcnt(0)
	v_readlane_b32 s19, v253, 0
	v_lshrrev_b32_e32 v4, 2, v218
	v_and_b32_e32 v5, 3, v218
	v_lshlrev_b32_e32 v6, 17, v4
	v_lshl_add_u32 v6, v5, 6, v6
	v_mul_u32_u24_e32 v7, 4352, v5
	v_lshl_add_u32 v7, v4, 2, v7
	v_mul_u32_u24_e32 v8, 272, v4
	v_lshl_add_u32 v8, v5, 6, v8
	v_lshlrev_b32_e32 v9, 9, v4
	v_lshl_add_u32 v9, v5, 5, v9
	v_lshlrev_b32_e32 v10, 11, v4
	v_lshl_add_u32 v10, v5, 5, v10
	v_lshlrev_b32_e32 v12, 14, v4
	v_lshl_add_u32 v12, v5, 6, v12
	v_mov_b32_e32 v13, v6
	s_mov_b32 s38, 0
; DI u16 f2bf(float x) { u32 u = __float_as_uint(x); u += 0x7fffu + ((u >> 16) & 1u); return (u16)(u >> 16); }
; DI float bf2f(u16 v) { return __uint_as_float(((u32)v) << 16); }
; DI void hyena_item(const Params& p, int l, int it) {
;     ...
;   const int b = l16;
; #pragma unroll
;   for (int i = 0; i < 4; ++i)
; #pragma unroll
;     for (int r = 0; r < 4; ++r) {
;       const int t = tt0 + 16 * i + kg * 4 + r;
;       const size_t row = (size_t)b * TPB + posoff + t;
;       const float u = bf2f(UT[((size_t)(c * 16 + b)) * TPB + posoff + t]);
;       const float x1 = bf2f(X1C[row * 256 + c]);
;       YM[row * 1024 + c] = f2bf(x1 * (scale * acc[i][r] + bias * u));
;     }
.Lhyt_top:
	s_cmp_eq_u32 s38, 4
	s_cbranch_scc1 .Lhyt_ctx
	s_lshl_b32 s16, s38, 9
	s_add_i32 s16, s16, s19
	s_and_b32 s22, s16, 3
	s_bfe_u32 s23, s16, 0x50002
	s_lshr_b32 s25, s16, 7
	s_lshl_b32 s17, s22, 23
	s_lshl_b32 s16, s25, 13
	s_add_i32 s17, s17, s16
	s_lshl_b32 s16, s23, 8
	s_add_i32 s17, s17, s16
	s_add_u32 s26, s96, s17
	s_addc_u32 s27, s97, 0
	s_mul_i32 s17, s25, 0x900
	s_lshl_b32 s16, s23, 6
	s_add_i32 s17, s17, s16
	s_addk_i32 s17, 0x100
	s_branch .Lhyt_go
.Lhyt_ctx:
	s_and_b32 s22, s19, 3
	s_bfe_u32 s23, s19, 0x20002
	s_lshr_b32 s25, s19, 4
	s_lshl_b32 s17, s22, 20
	s_lshl_b32 s16, s25, 10
	s_add_i32 s17, s17, s16
	s_lshl_b32 s16, s23, 8
	s_add_i32 s17, s17, s16
	s_add_u32 s17, s17, 0x2000000
	s_add_u32 s26, s96, s17
	s_addc_u32 s27, s97, 0
	s_mul_i32 s17, s25, 0x900
	s_lshl_b32 s16, s23, 6
	s_add_i32 s17, s17, s16
	v_mov_b32_e32 v13, v12
.Lhyt_go:
	s_lshl_b32 s16, s17, 9
	s_lshl_b32 s39, s22, 7
	s_add_i32 s16, s16, s39
	s_add_u32 s28, s96, 0x16800000
	s_addc_u32 s29, s97, 0
	s_add_u32 s28, s28, s16
	s_addc_u32 s29, s29, 0
	s_lshl_b32 s16, s17, 11
	s_add_i32 s16, s16, s39
	s_add_u32 s30, s6, s16
	s_addc_u32 s31, s7, 0
	global_load_dwordx4 v[16:19], v13, s[26:27]
	global_load_dwordx4 v[20:23], v13, s[26:27] offset:16
	global_load_dwordx4 v[24:27], v13, s[26:27] offset:32
	global_load_dwordx4 v[28:31], v13, s[26:27] offset:48
	global_load_dwordx4 v[32:35], v9, s[28:29]
	global_load_dwordx4 v[36:39], v9, s[28:29] offset:16
	s_waitcnt vmcnt(2)
	ds_write_b32 v7, v16
	ds_write_b32 v7, v17 offset:272
	ds_write_b32 v7, v18 offset:544
	ds_write_b32 v7, v19 offset:816
	ds_write_b32 v7, v20 offset:1088
	ds_write_b32 v7, v21 offset:1360
	ds_write_b32 v7, v22 offset:1632
	ds_write_b32 v7, v23 offset:1904
	ds_write_b32 v7, v24 offset:2176
	ds_write_b32 v7, v25 offset:2448
	ds_write_b32 v7, v26 offset:2720
	ds_write_b32 v7, v27 offset:2992
	ds_write_b32 v7, v28 offset:3264
	ds_write_b32 v7, v29 offset:3536
	ds_write_b32 v7, v30 offset:3808
	ds_write_b32 v7, v31 offset:4080
	s_waitcnt lgkmcnt(0)
	s_barrier
	ds_read_b128 v[16:19], v8
	ds_read_b128 v[20:23], v8 offset:16
	ds_read_b128 v[24:27], v8 offset:32
	ds_read_b128 v[28:31], v8 offset:48
	s_waitcnt vmcnt(0) lgkmcnt(0)
	v_lshlrev_b32_e32 v11, 16, v32
	v_mul_f32_e32 v16, v16, v11
	v_and_b32_e32 v11, 0xffff0000, v32
	v_mul_f32_e32 v17, v17, v11
	v_lshlrev_b32_e32 v11, 16, v33
	v_mul_f32_e32 v18, v18, v11
	v_and_b32_e32 v11, 0xffff0000, v33
	v_mul_f32_e32 v19, v19, v11
	v_lshlrev_b32_e32 v11, 16, v34
	v_mul_f32_e32 v20, v20, v11
	v_and_b32_e32 v11, 0xffff0000, v34
	v_mul_f32_e32 v21, v21, v11
	v_lshlrev_b32_e32 v11, 16, v35
	v_mul_f32_e32 v22, v22, v11
	v_and_b32_e32 v11, 0xffff0000, v35
	v_mul_f32_e32 v23, v23, v11
	v_lshlrev_b32_e32 v11, 16, v36
	v_mul_f32_e32 v24, v24, v11
	v_and_b32_e32 v11, 0xffff0000, v36
	v_mul_f32_e32 v25, v25, v11
	v_lshlrev_b32_e32 v11, 16, v37
	v_mul_f32_e32 v26, v26, v11
	v_and_b32_e32 v11, 0xffff0000, v37
	v_mul_f32_e32 v27, v27, v11
	v_lshlrev_b32_e32 v11, 16, v38
	v_mul_f32_e32 v28, v28, v11
	v_and_b32_e32 v11, 0xffff0000, v38
	v_mul_f32_e32 v29, v29, v11
	v_lshlrev_b32_e32 v11, 16, v39
	v_mul_f32_e32 v30, v30, v11
	v_and_b32_e32 v11, 0xffff0000, v39
	v_mul_f32_e32 v31, v31, v11
	v_cvt_pk_bf16_f32 v32, v16, v17
	v_cvt_pk_bf16_f32 v33, v18, v19
	v_cvt_pk_bf16_f32 v34, v20, v21
	v_cvt_pk_bf16_f32 v35, v22, v23
	v_cvt_pk_bf16_f32 v36, v24, v25
	v_cvt_pk_bf16_f32 v37, v26, v27
	v_cvt_pk_bf16_f32 v38, v28, v29
	v_cvt_pk_bf16_f32 v39, v30, v31
	s_nop 0
	global_store_dwordx4 v10, v[32:35], s[30:31]
	global_store_dwordx4 v10, v[36:39], s[30:31] offset:16
	s_barrier
	s_add_i32 s38, s38, 1
	s_cmp_lt_u32 s38, 4
	s_cbranch_scc1 .Lhyt_top
	s_cmp_eq_u32 s38, 4
	s_cselect_b32 s16, 1, 0
	s_cmpk_lt_u32 s19, 0x100
	s_cselect_b32 s17, 1, 0
	s_and_b32 s16, s16, s17
	s_cmp_lg_u32 s16, 0
	s_cbranch_scc1 .Lhyt_top
	s_waitcnt vmcnt(0)
